# P5 start: the four QK-norm gain loads of the score-bound check issued together (two serialized round trips removed)
# speedup vs baseline: 1.0005x; 1.0005x over previous
.LBB0_1206:
	s_cmp_gt_i32 s80, 5
	s_cselect_b64 s[0:1], -1, 0
	s_cmp_lt_i32 s81, 6
	s_cselect_b64 s[4:5], -1, 0
	s_or_b64 s[0:1], s[0:1], s[4:5]
	s_and_b64 vcc, exec, s[0:1]
	v_lshlrev_b32_e32 v170, 2, v252
	s_cbranch_vccnz .LBB0_1310
	s_load_dwordx2 s[98:99], s[96:97], 0x60
	s_load_dwordx2 s[8:9], s[96:97], 0x68
	v_mov_b32_e32 v171, 0
	v_cmp_gt_u32_e64 s[4:5], 32, v252
	v_mov_b32_e32 v2, 0
	v_mov_b32_e32 v4, 0
	s_waitcnt lgkmcnt(0)
	global_load_dword v1, v170, s[98:99]
	global_load_dword v3, v170, s[8:9]
	s_and_saveexec_b64 s[6:7], s[4:5]
	global_load_dword v2, v170, s[98:99] offset:256
	global_load_dword v4, v170, s[8:9] offset:256
	s_waitcnt vmcnt(0)
	v_and_b32_e32 v2, 0x7fffffff, v2
	v_and_b32_e32 v171, 0x7fffffff, v4
	s_or_b64 exec, exec, s[6:7]
	v_mbcnt_lo_u32_b32 v4, -1, 0
	v_mbcnt_hi_u32_b32 v4, -1, v4
	v_and_b32_e32 v5, 64, v4
	v_add_u32_e32 v5, 64, v5
	v_xor_b32_e32 v6, 1, v4
	v_cmp_lt_i32_e32 vcc, v6, v5
	v_max_f32_e32 v2, v2, v2
	s_waitcnt vmcnt(0)
	v_max_f32_e64 v1, |v1|, |v1|
	v_cndmask_b32_e32 v6, v4, v6, vcc
	v_max_f32_e32 v1, v1, v2
	v_lshlrev_b32_e32 v6, 2, v6
	ds_bpermute_b32 v7, v6, v1
	v_max_f32_e32 v2, v171, v171
	v_max_f32_e64 v3, |v3|, |v3|
	v_max_f32_e32 v2, v3, v2
	ds_bpermute_b32 v3, v6, v2
	s_waitcnt lgkmcnt(1)
	v_max_f32_e32 v6, v7, v7
	v_max_f32_e32 v1, v1, v6
	v_xor_b32_e32 v6, 2, v4
	v_cmp_lt_i32_e32 vcc, v6, v5
	s_waitcnt lgkmcnt(0)
	v_max_f32_e32 v3, v3, v3
	v_max_f32_e32 v2, v2, v3
	v_cndmask_b32_e32 v6, v4, v6, vcc
	v_lshlrev_b32_e32 v6, 2, v6
	ds_bpermute_b32 v7, v6, v1
	ds_bpermute_b32 v3, v6, v2
	s_mov_b32 s0, 0x42200000
	v_readlane_b32 s2, v255, 2
	v_and_b32_e32 v172, 31, v0
	s_waitcnt lgkmcnt(1)
	v_max_f32_e32 v6, v7, v7
	v_max_f32_e32 v1, v1, v6
	v_xor_b32_e32 v6, 4, v4
	v_cmp_lt_i32_e32 vcc, v6, v5
	s_waitcnt lgkmcnt(0)
	v_max_f32_e32 v3, v3, v3
	v_max_f32_e32 v2, v2, v3
	v_cndmask_b32_e32 v6, v4, v6, vcc
	v_lshlrev_b32_e32 v6, 2, v6
	ds_bpermute_b32 v7, v6, v1
	ds_bpermute_b32 v3, v6, v2
	v_lshrrev_b32_e32 v10, 1, v0
	v_bfe_u32 v11, v0, 1, 3
	v_lshlrev_b32_e32 v9, 4, v172
	s_waitcnt lgkmcnt(1)
	v_max_f32_e32 v6, v7, v7
	v_max_f32_e32 v1, v1, v6
	v_xor_b32_e32 v6, 8, v4
	v_cmp_lt_i32_e32 vcc, v6, v5
	s_waitcnt lgkmcnt(0)
	v_max_f32_e32 v3, v3, v3
	v_max_f32_e32 v2, v2, v3
	v_cndmask_b32_e32 v6, v4, v6, vcc
	v_lshlrev_b32_e32 v6, 2, v6
	ds_bpermute_b32 v7, v6, v1
	ds_bpermute_b32 v3, v6, v2
	s_mov_b32 s9, 0
	s_mov_b64 s[48:49], -1
	v_mov_b32_e32 v175, 0
	s_waitcnt lgkmcnt(1)
	v_max_f32_e32 v6, v7, v7
	v_max_f32_e32 v1, v1, v6
	v_xor_b32_e32 v6, 16, v4
	v_cmp_lt_i32_e32 vcc, v6, v5
	s_waitcnt lgkmcnt(0)
	v_max_f32_e32 v3, v3, v3
	v_max_f32_e32 v2, v2, v3
	v_cndmask_b32_e32 v6, v4, v6, vcc
	v_lshlrev_b32_e32 v6, 2, v6
	ds_bpermute_b32 v7, v6, v1
	ds_bpermute_b32 v3, v6, v2
	v_lshlrev_b32_e32 v171, 6, v252
	v_lshrrev_b32_e32 v179, 3, v252
	v_lshrrev_b32_e32 v180, 2, v252
	s_waitcnt lgkmcnt(1)
	v_max_f32_e32 v6, v7, v7
	v_max_f32_e32 v1, v1, v6
	v_xor_b32_e32 v6, 32, v4
	v_cmp_lt_i32_e32 vcc, v6, v5
	s_waitcnt lgkmcnt(0)
	v_max_f32_e32 v3, v3, v3
	v_max_f32_e32 v2, v2, v3
	v_cndmask_b32_e32 v4, v4, v6, vcc
	v_lshlrev_b32_e32 v4, 2, v4
	ds_bpermute_b32 v5, v4, v1
	ds_bpermute_b32 v3, v4, v2
	v_lshlrev_b32_e32 v6, 4, v0
	v_and_b32_e32 v7, 0xc0, v6
	v_bitop3_b32 v181, v6, 48, v0 bitop3:0x48
	s_waitcnt lgkmcnt(1)
	v_max_f32_e32 v4, v5, v5
	v_max_f32_e32 v1, v1, v4
	s_waitcnt lgkmcnt(0)
	v_max_f32_e32 v3, v3, v3
	v_max_f32_e32 v2, v2, v3
	v_mul_f32_e32 v1, 0x411cc471, v1
	v_mul_f32_e32 v1, v2, v1
	v_mul_f32_e32 v1, 0x3fb8aa3b, v1
	v_mov_b32_e32 v2, 1.0
	v_fmamk_f32 v1, v1, 0x3f828f5c, v2
	v_cmp_ge_f32_e32 vcc, s0, v1
	v_lshlrev_b32_e32 v4, 3, v0
	v_and_b32_e32 v4, 24, v4
	v_cndmask_b32_e64 v1, 0, 1, vcc
	v_lshlrev_b32_e32 v3, 8, v0
	v_readfirstlane_b32 s0, v1
	s_bitcmp1_b32 s0, 0
	s_cselect_b64 s[0:1], -1, 0
	s_xor_b64 s[46:47], s[0:1], -1
	v_or_b32_e32 v173, 64, v4
	s_movk_i32 s0, 0x3c00
	v_and_or_b32 v177, v3, s0, v173
	s_lshr_b32 s0, s2, 4
	s_and_b32 s74, s0, 6
	s_ashr_i32 s0, s2, 7
	s_ashr_i32 s1, s0, 31
	s_lshl_b32 s2, s2, 8
	s_lshl_b64 s[50:51], s[0:1], 13
	s_and_b32 s2, s2, 0x1f00
	s_or_b32 s50, s50, s2
	s_lshl_b64 s[6:7], s[0:1], 24
	s_add_u32 s75, s60, s6
	s_addc_u32 s76, s61, s7
	s_lshl_b64 s[0:1], s[0:1], 19
	s_add_u32 s52, s92, s0
	s_addc_u32 s53, s93, s1
	s_add_u32 s54, s52, 0x1000
	v_lshrrev_b32_e32 v2, 5, v252
	s_addc_u32 s55, s53, 0
	v_lshlrev_b32_e32 v6, 7, v172
	v_bitop3_b32 v10, v2, v10, 7 bitop3:0x78
	s_add_u32 s56, s52, 0x2000
	v_lshl_or_b32 v182, v10, 4, v6
	v_bitop3_b32 v10, v2, v11, 2 bitop3:0x36
	s_addc_u32 s57, s53, 0
	v_lshl_or_b32 v183, v10, 4, v6
	v_bitop3_b32 v10, v2, v11, 4 bitop3:0x36
	s_add_u32 s58, s52, 0x3000
	v_lshlrev_b32_e32 v3, 1, v0
	v_lshl_or_b32 v184, v10, 4, v6
	v_bitop3_b32 v10, v2, v11, 6 bitop3:0x36
	s_addc_u32 s59, s53, 0
	v_and_b32_e32 v3, 32, v3
	v_lshl_or_b32 v185, v10, 4, v6
	v_lshrrev_b32_e32 v10, 2, v0
	v_bfe_u32 v11, v0, 2, 2
	s_add_u32 s60, s52, 0x4000
	v_lshlrev_b32_e32 v176, 3, v2
	v_lshlrev_b32_e32 v5, 8, v2
	v_lshlrev_b32_e32 v8, 10, v2
	v_lshlrev_b32_e32 v178, 4, v2
	v_lshlrev_b32_e32 v6, 6, v172
	v_bitop3_b32 v10, v2, v10, 3 bitop3:0x78
	v_bitop3_b32 v2, v2, v11, 2 bitop3:0x36
	v_or_b32_e32 v11, v7, v3
	s_addc_u32 s61, s53, 0
	v_or3_b32 v11, v11, v4, v5
	v_lshl_or_b32 v188, v2, 4, v6
	v_add3_u32 v2, 0, v3, v5
	s_add_u32 s62, s52, 0x5000
	v_lshlrev_b32_e32 v1, 11, v252
	v_add3_u32 v186, 0, v8, v9
	v_lshl_or_b32 v187, v10, 4, v6
	v_add_u32_e32 v189, 0, v11
	v_add3_u32 v190, v2, v7, v4
	s_addc_u32 s63, s53, 0
	s_movk_i32 s77, 0x600
	s_brev_b32 s16, 1
	s_mov_b32 s78, 0x41000000
	s_movk_i32 s79, 0x70
	s_mov_b32 s0, 0
	s_branch .LBB0_1214
